# new unrolled scalar-f32 scan loop (no v_pk), attention side now critical
# baseline (speedup 1.0000x reference)
; #define LAS __attribute__((address_space(3)))
;     __device__ __forceinline__ const float* in(int i) const { return (const float*)ptr(i); }
;     __device__ __forceinline__ float* out() const { return (float*)ptr(36); }
; __device__ __forceinline__ void scan_step(f32x4& S, const ScanOps& o, LAS float* yp) {
;     f32x2 S0 = {S[0], S[1]}, S1 = {S[2], S[3]};
;     const f32x2 k0 = {o.kk[0], o.kk[1]}, k1 = {o.kk[2], o.kk[3]};
;     f32x2 t = S0 * k0; t = S1 * k1 + t;
;     const float sa = -sum16(t[0] + t[1]);
;     const f32x2 sav = {sa, sa}, vv = {o.v, o.v};
;     const f32x2 a0 = {o.ka[0], o.ka[1]}, a1 = {o.ka[2], o.ka[3]}, p0 = {o.kp[0], o.kp[1]}, p1 = {o.kp[2], o.kp[3]}, w0 = {o.w[0], o.w[1]}, w1 = {o.w[2], o.w[3]};
;     f32x2 u0 = a0 * sav; u0 = p0 * vv + u0; S0 = S0 * w0 + u0;
;     f32x2 u1 = a1 * sav; u1 = p1 * vv + u1; S1 = S1 * w1 + u1;
;     const f32x2 r0 = {o.rr[0], o.rr[1]}, r1 = {o.rr[2], o.rr[3]};
;     f32x2 y = S0 * r0; y = S1 * r1 + y;
;     *yp = y[0] + y[1];
;     S = (f32x4){S0[0], S0[1], S1[0], S1[1]};
; __device__ __forceinline__ void scan_unit(const Ctx& p, int chain, int rq, LAS unsigned char* lds) {
;     ...
;         const int rl = lane >> 4, cl = lane & 15, il = 4 * wave + rl;
;         f32x4 S;
;         float* sg = (smp ? p.out() + O_SS : p.out() + O_SP) + ((size_t)(cb * 8 + h) * 64 + 16 * rq + il) * 64 + 4 * cl;
;         if (smp) S = *(const f32x4*)(p.in(4) + ((size_t)(cb * 8 + h) * 64 + 16 * rq + il) * 64 + 4 * cl); else S = (f32x4){0.f, 0.f, 0.f, 0.f};
;         for (int ci = 0; ci < nch; ++ci) {
;             __syncthreads();
;             const LAS float* OP = B0 + (ci & 1) * SBUF_F + 4 * cl;
;             const LAS float* VP = B0 + (ci & 1) * SBUF_F + SCH * 320 + il * 16;
;             LAS float* Y = YB + (ci & 1) * YP_F + il * 16 + cl;
;             ScanOps oa, ob;
;             scan_load(oa, OP, VP, 0);
;             f32x2 vv = *(const LAS f32x2*)VP;
; #pragma unroll 1
;             for (int t = 0; t < SCH; t += 2) {
;                 scan_load(ob, OP, VP, t + 1);
;                 oa.v = vv[0]; ob.v = vv[1];
;                 scan_step(S, oa, Y + t * 256);
;                 scan_load(oa, OP, VP, (t + 2) & (SCH - 1));
;                 vv = *(const LAS f32x2*)(VP + ((t + 2) & (SCH - 1)));
;                 scan_step(S, ob, Y + (t + 1) * 256);
;             }
.LBB0_1711:
	s_and_b64 vcc, exec, s[2:3]
	s_cbranch_vccz .LBB0_1750
	s_add_i32 s2, 0, 0x23528
	s_waitcnt vmcnt(0)
	v_mov_b32_e32 v0, s2
	ds_read_b64 v[0:1], v0
	v_readfirstlane_b32 s8, v180
	s_mov_b32 s10, 0
	s_cmpk_lt_u32 s8, 0x100
	s_mov_b64 s[2:3], -1
	s_waitcnt lgkmcnt(0)
	v_readfirstlane_b32 s4, v0
	v_readfirstlane_b32 s5, v1
	s_barrier
	s_cbranch_scc0 .LBB0_1718
	s_add_i32 s2, 0, 0x23520
	v_mov_b32_e32 v0, s2
	ds_read_b64 v[0:1], v0
	v_bfe_u32 v2, v180, 4, 2
	v_and_b32_e32 v3, 15, v180
	s_lshr_b32 s2, s8, 4
	s_lshl_b32 s8, s8, 2
	v_and_or_b32 v27, s2, 12, v2
	s_waitcnt lgkmcnt(0)
	v_readfirstlane_b32 s2, v0
	v_lshlrev_b32_e32 v26, 2, v3
	s_and_b32 s8, s8, 0x300
	v_lshlrev_b32_e32 v0, 6, v2
	v_or3_b32 v0, s8, v0, v26
	v_add_u32_e32 v0, 0, v0
	v_add_u32_e32 v29, 0xa800, v0
	v_lshl_add_u32 v0, v3, 4, 0
	v_add_u32_e32 v30, 0x500, v0
	v_mov_b32_e32 v0, 0
	v_readfirstlane_b32 s3, v1
	v_lshlrev_b32_e32 v28, 4, v27
	s_mov_b64 s[8:9], 0
	s_movk_i32 s11, 0x5400
	v_mov_b32_e32 v1, v0
	v_mov_b32_e32 v2, v0
	v_mov_b32_e32 v3, v0
	s_setprio 2
.LBB0_1714:
	s_and_b32 s12, s10, 1
	s_mulk_i32 s12, 0x5400
	s_lshl_b32 s13, s10, 14
	v_lshl_add_u32 v31, v26, 2, s12
	s_and_b32 s13, s13, 0x4000
	v_lshl_add_u32 v32, v28, 2, s12
	v_add_u32_e32 v33, s13, v29
	s_waitcnt lgkmcnt(0)
	s_barrier
	ds_read_b128 v[40:43], v32 offset:20480
	ds_read_b128 v[44:47], v32 offset:20496
	ds_read_b128 v[48:51], v32 offset:20512
	ds_read_b128 v[52:55], v32 offset:20528
	ds_read_b128 v[60:63], v31 offset:256
	ds_read_b128 v[64:67], v31 offset:768
	ds_read_b128 v[68:71], v31 offset:0
	ds_read_b128 v[72:75], v31 offset:512
	ds_read_b128 v[76:79], v31 offset:1024
	ds_read_b128 v[80:83], v31 offset:1536
	ds_read_b128 v[84:87], v31 offset:2048
	ds_read_b128 v[88:91], v31 offset:1280
	ds_read_b128 v[92:95], v31 offset:1792
	ds_read_b128 v[96:99], v31 offset:2304
	s_waitcnt lgkmcnt(5)
	v_mul_f32_e32 v100, v0, v60
	v_fmac_f32_e32 v100, v1, v61
	v_fmac_f32_e32 v100, v2, v62
	v_fmac_f32_e32 v100, v3, v63
	v_mul_f32_e32 v104, v64, v40
	v_mul_f32_e32 v105, v65, v40
	v_add_f32_dpp v100, v100, v100 quad_perm:[1,0,3,2] row_mask:0xf bank_mask:0xf bound_ctrl:1
	v_mul_f32_e32 v106, v66, v40
	v_mul_f32_e32 v107, v67, v40
	v_add_f32_dpp v100, v100, v100 quad_perm:[2,3,0,1] row_mask:0xf bank_mask:0xf bound_ctrl:1
	v_fmac_f32_e32 v104, v0, v68
	v_fmac_f32_e32 v105, v1, v69
	v_add_f32_dpp v100, v100, v100 row_half_mirror row_mask:0xf bank_mask:0xf bound_ctrl:1
	v_fmac_f32_e32 v106, v2, v70
	v_fmac_f32_e32 v107, v3, v71
	v_add_f32_dpp v100, v100, v100 row_mirror row_mask:0xf bank_mask:0xf bound_ctrl:1
	v_fma_f32 v0, -v72, v100, v104
	v_fma_f32 v1, -v73, v100, v105
	v_fma_f32 v2, -v74, v100, v106
	v_fma_f32 v3, -v75, v100, v107
	v_mul_f32_e32 v101, v0, v76
	v_fmac_f32_e32 v101, v1, v77
	v_fmac_f32_e32 v101, v2, v78
	v_fmac_f32_e32 v101, v3, v79
	ds_write_b32 v33, v101 offset:0
	ds_read_b128 v[60:63], v31 offset:2816
	ds_read_b128 v[64:67], v31 offset:3328
	ds_read_b128 v[68:71], v31 offset:2560
	ds_read_b128 v[72:75], v31 offset:3072
	ds_read_b128 v[76:79], v31 offset:3584
	s_waitcnt lgkmcnt(6)
	v_mul_f32_e32 v100, v0, v80
	v_fmac_f32_e32 v100, v1, v81
	v_fmac_f32_e32 v100, v2, v82
	v_fmac_f32_e32 v100, v3, v83
	v_mul_f32_e32 v104, v84, v41
	v_mul_f32_e32 v105, v85, v41
	v_add_f32_dpp v100, v100, v100 quad_perm:[1,0,3,2] row_mask:0xf bank_mask:0xf bound_ctrl:1
	v_mul_f32_e32 v106, v86, v41
	v_mul_f32_e32 v107, v87, v41
	v_add_f32_dpp v100, v100, v100 quad_perm:[2,3,0,1] row_mask:0xf bank_mask:0xf bound_ctrl:1
	v_fmac_f32_e32 v104, v0, v88
	v_fmac_f32_e32 v105, v1, v89
	v_add_f32_dpp v100, v100, v100 row_half_mirror row_mask:0xf bank_mask:0xf bound_ctrl:1
	v_fmac_f32_e32 v106, v2, v90
	v_fmac_f32_e32 v107, v3, v91
	v_add_f32_dpp v100, v100, v100 row_mirror row_mask:0xf bank_mask:0xf bound_ctrl:1
	v_fma_f32 v0, -v92, v100, v104
	v_fma_f32 v1, -v93, v100, v105
	v_fma_f32 v2, -v94, v100, v106
	v_fma_f32 v3, -v95, v100, v107
	v_mul_f32_e32 v101, v0, v96
	v_fmac_f32_e32 v101, v1, v97
	v_fmac_f32_e32 v101, v2, v98
	v_fmac_f32_e32 v101, v3, v99
	ds_write_b32 v33, v101 offset:1024
	ds_read_b128 v[80:83], v31 offset:4096
	ds_read_b128 v[84:87], v31 offset:4608
	ds_read_b128 v[88:91], v31 offset:3840
	ds_read_b128 v[92:95], v31 offset:4352
	ds_read_b128 v[96:99], v31 offset:4864
	s_waitcnt lgkmcnt(6)
	v_mul_f32_e32 v100, v0, v60
	v_fmac_f32_e32 v100, v1, v61
	v_fmac_f32_e32 v100, v2, v62
	v_fmac_f32_e32 v100, v3, v63
	v_mul_f32_e32 v104, v64, v42
	v_mul_f32_e32 v105, v65, v42
	v_add_f32_dpp v100, v100, v100 quad_perm:[1,0,3,2] row_mask:0xf bank_mask:0xf bound_ctrl:1
	v_mul_f32_e32 v106, v66, v42
	v_mul_f32_e32 v107, v67, v42
	v_add_f32_dpp v100, v100, v100 quad_perm:[2,3,0,1] row_mask:0xf bank_mask:0xf bound_ctrl:1
	v_fmac_f32_e32 v104, v0, v68
	v_fmac_f32_e32 v105, v1, v69
	v_add_f32_dpp v100, v100, v100 row_half_mirror row_mask:0xf bank_mask:0xf bound_ctrl:1
	v_fmac_f32_e32 v106, v2, v70
	v_fmac_f32_e32 v107, v3, v71
	v_add_f32_dpp v100, v100, v100 row_mirror row_mask:0xf bank_mask:0xf bound_ctrl:1
	v_fma_f32 v0, -v72, v100, v104
	v_fma_f32 v1, -v73, v100, v105
	v_fma_f32 v2, -v74, v100, v106
	v_fma_f32 v3, -v75, v100, v107
	v_mul_f32_e32 v101, v0, v76
	v_fmac_f32_e32 v101, v1, v77
	v_fmac_f32_e32 v101, v2, v78
	v_fmac_f32_e32 v101, v3, v79
	ds_write_b32 v33, v101 offset:2048
	ds_read_b128 v[60:63], v31 offset:5376
	ds_read_b128 v[64:67], v31 offset:5888
	ds_read_b128 v[68:71], v31 offset:5120
	ds_read_b128 v[72:75], v31 offset:5632
	ds_read_b128 v[76:79], v31 offset:6144
	s_waitcnt lgkmcnt(6)
; #define LAS __attribute__((address_space(3)))
; __device__ __forceinline__ float sum16(float x) { x = dpp_add<0xB1>(x); x = dpp_add<0x4E>(x); x = dpp_add<0x141>(x); x = dpp_add<0x140>(x); return x; }
; __device__ __forceinline__ void scan_step(f32x4& S, const ScanOps& o, LAS float* yp) {
;     f32x2 S0 = {S[0], S[1]}, S1 = {S[2], S[3]};
;     const f32x2 k0 = {o.kk[0], o.kk[1]}, k1 = {o.kk[2], o.kk[3]};
;     f32x2 t = S0 * k0; t = S1 * k1 + t;
;     const float sa = -sum16(t[0] + t[1]);
;     const f32x2 sav = {sa, sa}, vv = {o.v, o.v};
;     const f32x2 a0 = {o.ka[0], o.ka[1]}, a1 = {o.ka[2], o.ka[3]}, p0 = {o.kp[0], o.kp[1]}, p1 = {o.kp[2], o.kp[3]}, w0 = {o.w[0], o.w[1]}, w1 = {o.w[2], o.w[3]};
;     f32x2 u0 = a0 * sav; u0 = p0 * vv + u0; S0 = S0 * w0 + u0;
;     f32x2 u1 = a1 * sav; u1 = p1 * vv + u1; S1 = S1 * w1 + u1;
;     const f32x2 r0 = {o.rr[0], o.rr[1]}, r1 = {o.rr[2], o.rr[3]};
;     f32x2 y = S0 * r0; y = S1 * r1 + y;
;     *yp = y[0] + y[1];
;     S = (f32x4){S0[0], S0[1], S1[0], S1[1]};
	v_mul_f32_e32 v100, v0, v80
	v_fmac_f32_e32 v100, v1, v81
	v_fmac_f32_e32 v100, v2, v82
	v_fmac_f32_e32 v100, v3, v83
	v_mul_f32_e32 v104, v84, v43
	v_mul_f32_e32 v105, v85, v43
	v_add_f32_dpp v100, v100, v100 quad_perm:[1,0,3,2] row_mask:0xf bank_mask:0xf bound_ctrl:1
	v_mul_f32_e32 v106, v86, v43
	v_mul_f32_e32 v107, v87, v43
	v_add_f32_dpp v100, v100, v100 quad_perm:[2,3,0,1] row_mask:0xf bank_mask:0xf bound_ctrl:1
	v_fmac_f32_e32 v104, v0, v88
	v_fmac_f32_e32 v105, v1, v89
	v_add_f32_dpp v100, v100, v100 row_half_mirror row_mask:0xf bank_mask:0xf bound_ctrl:1
	v_fmac_f32_e32 v106, v2, v90
	v_fmac_f32_e32 v107, v3, v91
	v_add_f32_dpp v100, v100, v100 row_mirror row_mask:0xf bank_mask:0xf bound_ctrl:1
	v_fma_f32 v0, -v92, v100, v104
	v_fma_f32 v1, -v93, v100, v105
	v_fma_f32 v2, -v94, v100, v106
	v_fma_f32 v3, -v95, v100, v107
	v_mul_f32_e32 v101, v0, v96
	v_fmac_f32_e32 v101, v1, v97
	v_fmac_f32_e32 v101, v2, v98
	v_fmac_f32_e32 v101, v3, v99
	ds_write_b32 v33, v101 offset:3072
	ds_read_b128 v[80:83], v31 offset:6656
	ds_read_b128 v[84:87], v31 offset:7168
	ds_read_b128 v[88:91], v31 offset:6400
	ds_read_b128 v[92:95], v31 offset:6912
	ds_read_b128 v[96:99], v31 offset:7424
	s_waitcnt lgkmcnt(6)
	v_mul_f32_e32 v100, v0, v60
	v_fmac_f32_e32 v100, v1, v61
	v_fmac_f32_e32 v100, v2, v62
	v_fmac_f32_e32 v100, v3, v63
	v_mul_f32_e32 v104, v64, v44
	v_mul_f32_e32 v105, v65, v44
	v_add_f32_dpp v100, v100, v100 quad_perm:[1,0,3,2] row_mask:0xf bank_mask:0xf bound_ctrl:1
	v_mul_f32_e32 v106, v66, v44
	v_mul_f32_e32 v107, v67, v44
	v_add_f32_dpp v100, v100, v100 quad_perm:[2,3,0,1] row_mask:0xf bank_mask:0xf bound_ctrl:1
	v_fmac_f32_e32 v104, v0, v68
	v_fmac_f32_e32 v105, v1, v69
	v_add_f32_dpp v100, v100, v100 row_half_mirror row_mask:0xf bank_mask:0xf bound_ctrl:1
	v_fmac_f32_e32 v106, v2, v70
	v_fmac_f32_e32 v107, v3, v71
	v_add_f32_dpp v100, v100, v100 row_mirror row_mask:0xf bank_mask:0xf bound_ctrl:1
	v_fma_f32 v0, -v72, v100, v104
	v_fma_f32 v1, -v73, v100, v105
	v_fma_f32 v2, -v74, v100, v106
	v_fma_f32 v3, -v75, v100, v107
	v_mul_f32_e32 v101, v0, v76
	v_fmac_f32_e32 v101, v1, v77
	v_fmac_f32_e32 v101, v2, v78
	v_fmac_f32_e32 v101, v3, v79
	ds_write_b32 v33, v101 offset:4096
	ds_read_b128 v[60:63], v31 offset:7936
	ds_read_b128 v[64:67], v31 offset:8448
	ds_read_b128 v[68:71], v31 offset:7680
	ds_read_b128 v[72:75], v31 offset:8192
	ds_read_b128 v[76:79], v31 offset:8704
	s_waitcnt lgkmcnt(6)
	v_mul_f32_e32 v100, v0, v80
	v_fmac_f32_e32 v100, v1, v81
	v_fmac_f32_e32 v100, v2, v82
	v_fmac_f32_e32 v100, v3, v83
	v_mul_f32_e32 v104, v84, v45
	v_mul_f32_e32 v105, v85, v45
	v_add_f32_dpp v100, v100, v100 quad_perm:[1,0,3,2] row_mask:0xf bank_mask:0xf bound_ctrl:1
	v_mul_f32_e32 v106, v86, v45
	v_mul_f32_e32 v107, v87, v45
	v_add_f32_dpp v100, v100, v100 quad_perm:[2,3,0,1] row_mask:0xf bank_mask:0xf bound_ctrl:1
	v_fmac_f32_e32 v104, v0, v88
	v_fmac_f32_e32 v105, v1, v89
	v_add_f32_dpp v100, v100, v100 row_half_mirror row_mask:0xf bank_mask:0xf bound_ctrl:1
	v_fmac_f32_e32 v106, v2, v90
	v_fmac_f32_e32 v107, v3, v91
	v_add_f32_dpp v100, v100, v100 row_mirror row_mask:0xf bank_mask:0xf bound_ctrl:1
	v_fma_f32 v0, -v92, v100, v104
	v_fma_f32 v1, -v93, v100, v105
	v_fma_f32 v2, -v94, v100, v106
	v_fma_f32 v3, -v95, v100, v107
	v_mul_f32_e32 v101, v0, v96
	v_fmac_f32_e32 v101, v1, v97
	v_fmac_f32_e32 v101, v2, v98
	v_fmac_f32_e32 v101, v3, v99
	ds_write_b32 v33, v101 offset:5120
	ds_read_b128 v[80:83], v31 offset:9216
	ds_read_b128 v[84:87], v31 offset:9728
	ds_read_b128 v[88:91], v31 offset:8960
	ds_read_b128 v[92:95], v31 offset:9472
	ds_read_b128 v[96:99], v31 offset:9984
	s_waitcnt lgkmcnt(6)
	v_mul_f32_e32 v100, v0, v60
	v_fmac_f32_e32 v100, v1, v61
	v_fmac_f32_e32 v100, v2, v62
	v_fmac_f32_e32 v100, v3, v63
	v_mul_f32_e32 v104, v64, v46
	v_mul_f32_e32 v105, v65, v46
	v_add_f32_dpp v100, v100, v100 quad_perm:[1,0,3,2] row_mask:0xf bank_mask:0xf bound_ctrl:1
	v_mul_f32_e32 v106, v66, v46
	v_mul_f32_e32 v107, v67, v46
	v_add_f32_dpp v100, v100, v100 quad_perm:[2,3,0,1] row_mask:0xf bank_mask:0xf bound_ctrl:1
	v_fmac_f32_e32 v104, v0, v68
	v_fmac_f32_e32 v105, v1, v69
	v_add_f32_dpp v100, v100, v100 row_half_mirror row_mask:0xf bank_mask:0xf bound_ctrl:1
	v_fmac_f32_e32 v106, v2, v70
	v_fmac_f32_e32 v107, v3, v71
	v_add_f32_dpp v100, v100, v100 row_mirror row_mask:0xf bank_mask:0xf bound_ctrl:1
	v_fma_f32 v0, -v72, v100, v104
	v_fma_f32 v1, -v73, v100, v105
	v_fma_f32 v2, -v74, v100, v106
	v_fma_f32 v3, -v75, v100, v107
	v_mul_f32_e32 v101, v0, v76
	v_fmac_f32_e32 v101, v1, v77
	v_fmac_f32_e32 v101, v2, v78
	v_fmac_f32_e32 v101, v3, v79
	ds_write_b32 v33, v101 offset:6144
	ds_read_b128 v[60:63], v31 offset:10496
	ds_read_b128 v[64:67], v31 offset:11008
	ds_read_b128 v[68:71], v31 offset:10240
	ds_read_b128 v[72:75], v31 offset:10752
	ds_read_b128 v[76:79], v31 offset:11264
	s_waitcnt lgkmcnt(6)
	v_mul_f32_e32 v100, v0, v80
	v_fmac_f32_e32 v100, v1, v81
	v_fmac_f32_e32 v100, v2, v82
	v_fmac_f32_e32 v100, v3, v83
	v_mul_f32_e32 v104, v84, v47
	v_mul_f32_e32 v105, v85, v47
	v_add_f32_dpp v100, v100, v100 quad_perm:[1,0,3,2] row_mask:0xf bank_mask:0xf bound_ctrl:1
	v_mul_f32_e32 v106, v86, v47
	v_mul_f32_e32 v107, v87, v47
	v_add_f32_dpp v100, v100, v100 quad_perm:[2,3,0,1] row_mask:0xf bank_mask:0xf bound_ctrl:1
	v_fmac_f32_e32 v104, v0, v88
	v_fmac_f32_e32 v105, v1, v89
	v_add_f32_dpp v100, v100, v100 row_half_mirror row_mask:0xf bank_mask:0xf bound_ctrl:1
	v_fmac_f32_e32 v106, v2, v90
	v_fmac_f32_e32 v107, v3, v91
	v_add_f32_dpp v100, v100, v100 row_mirror row_mask:0xf bank_mask:0xf bound_ctrl:1
	v_fma_f32 v0, -v92, v100, v104
	v_fma_f32 v1, -v93, v100, v105
	v_fma_f32 v2, -v94, v100, v106
	v_fma_f32 v3, -v95, v100, v107
	v_mul_f32_e32 v101, v0, v96
	v_fmac_f32_e32 v101, v1, v97
	v_fmac_f32_e32 v101, v2, v98
	v_fmac_f32_e32 v101, v3, v99
	ds_write_b32 v33, v101 offset:7168
	ds_read_b128 v[80:83], v31 offset:11776
	ds_read_b128 v[84:87], v31 offset:12288
	ds_read_b128 v[88:91], v31 offset:11520
	ds_read_b128 v[92:95], v31 offset:12032
	ds_read_b128 v[96:99], v31 offset:12544
	s_waitcnt lgkmcnt(6)
; #define LAS __attribute__((address_space(3)))
; __device__ __forceinline__ float sum16(float x) { x = dpp_add<0xB1>(x); x = dpp_add<0x4E>(x); x = dpp_add<0x141>(x); x = dpp_add<0x140>(x); return x; }
; __device__ __forceinline__ void scan_step(f32x4& S, const ScanOps& o, LAS float* yp) {
;     f32x2 S0 = {S[0], S[1]}, S1 = {S[2], S[3]};
;     const f32x2 k0 = {o.kk[0], o.kk[1]}, k1 = {o.kk[2], o.kk[3]};
;     f32x2 t = S0 * k0; t = S1 * k1 + t;
;     const float sa = -sum16(t[0] + t[1]);
;     const f32x2 sav = {sa, sa}, vv = {o.v, o.v};
;     const f32x2 a0 = {o.ka[0], o.ka[1]}, a1 = {o.ka[2], o.ka[3]}, p0 = {o.kp[0], o.kp[1]}, p1 = {o.kp[2], o.kp[3]}, w0 = {o.w[0], o.w[1]}, w1 = {o.w[2], o.w[3]};
;     f32x2 u0 = a0 * sav; u0 = p0 * vv + u0; S0 = S0 * w0 + u0;
;     f32x2 u1 = a1 * sav; u1 = p1 * vv + u1; S1 = S1 * w1 + u1;
;     const f32x2 r0 = {o.rr[0], o.rr[1]}, r1 = {o.rr[2], o.rr[3]};
;     f32x2 y = S0 * r0; y = S1 * r1 + y;
;     *yp = y[0] + y[1];
;     S = (f32x4){S0[0], S0[1], S1[0], S1[1]};
	v_mul_f32_e32 v100, v0, v60
	v_fmac_f32_e32 v100, v1, v61
	v_fmac_f32_e32 v100, v2, v62
	v_fmac_f32_e32 v100, v3, v63
	v_mul_f32_e32 v104, v64, v48
	v_mul_f32_e32 v105, v65, v48
	v_add_f32_dpp v100, v100, v100 quad_perm:[1,0,3,2] row_mask:0xf bank_mask:0xf bound_ctrl:1
	v_mul_f32_e32 v106, v66, v48
	v_mul_f32_e32 v107, v67, v48
	v_add_f32_dpp v100, v100, v100 quad_perm:[2,3,0,1] row_mask:0xf bank_mask:0xf bound_ctrl:1
	v_fmac_f32_e32 v104, v0, v68
	v_fmac_f32_e32 v105, v1, v69
	v_add_f32_dpp v100, v100, v100 row_half_mirror row_mask:0xf bank_mask:0xf bound_ctrl:1
	v_fmac_f32_e32 v106, v2, v70
	v_fmac_f32_e32 v107, v3, v71
	v_add_f32_dpp v100, v100, v100 row_mirror row_mask:0xf bank_mask:0xf bound_ctrl:1
	v_fma_f32 v0, -v72, v100, v104
	v_fma_f32 v1, -v73, v100, v105
	v_fma_f32 v2, -v74, v100, v106
	v_fma_f32 v3, -v75, v100, v107
	v_mul_f32_e32 v101, v0, v76
	v_fmac_f32_e32 v101, v1, v77
	v_fmac_f32_e32 v101, v2, v78
	v_fmac_f32_e32 v101, v3, v79
	ds_write_b32 v33, v101 offset:8192
	ds_read_b128 v[60:63], v31 offset:13056
	ds_read_b128 v[64:67], v31 offset:13568
	ds_read_b128 v[68:71], v31 offset:12800
	ds_read_b128 v[72:75], v31 offset:13312
	ds_read_b128 v[76:79], v31 offset:13824
	s_waitcnt lgkmcnt(6)
	v_mul_f32_e32 v100, v0, v80
	v_fmac_f32_e32 v100, v1, v81
	v_fmac_f32_e32 v100, v2, v82
	v_fmac_f32_e32 v100, v3, v83
	v_mul_f32_e32 v104, v84, v49
	v_mul_f32_e32 v105, v85, v49
	v_add_f32_dpp v100, v100, v100 quad_perm:[1,0,3,2] row_mask:0xf bank_mask:0xf bound_ctrl:1
	v_mul_f32_e32 v106, v86, v49
	v_mul_f32_e32 v107, v87, v49
	v_add_f32_dpp v100, v100, v100 quad_perm:[2,3,0,1] row_mask:0xf bank_mask:0xf bound_ctrl:1
	v_fmac_f32_e32 v104, v0, v88
	v_fmac_f32_e32 v105, v1, v89
	v_add_f32_dpp v100, v100, v100 row_half_mirror row_mask:0xf bank_mask:0xf bound_ctrl:1
	v_fmac_f32_e32 v106, v2, v90
	v_fmac_f32_e32 v107, v3, v91
	v_add_f32_dpp v100, v100, v100 row_mirror row_mask:0xf bank_mask:0xf bound_ctrl:1
	v_fma_f32 v0, -v92, v100, v104
	v_fma_f32 v1, -v93, v100, v105
	v_fma_f32 v2, -v94, v100, v106
	v_fma_f32 v3, -v95, v100, v107
	v_mul_f32_e32 v101, v0, v96
	v_fmac_f32_e32 v101, v1, v97
	v_fmac_f32_e32 v101, v2, v98
	v_fmac_f32_e32 v101, v3, v99
	ds_write_b32 v33, v101 offset:9216
	ds_read_b128 v[80:83], v31 offset:14336
	ds_read_b128 v[84:87], v31 offset:14848
	ds_read_b128 v[88:91], v31 offset:14080
	ds_read_b128 v[92:95], v31 offset:14592
	ds_read_b128 v[96:99], v31 offset:15104
	s_waitcnt lgkmcnt(6)
	v_mul_f32_e32 v100, v0, v60
	v_fmac_f32_e32 v100, v1, v61
	v_fmac_f32_e32 v100, v2, v62
	v_fmac_f32_e32 v100, v3, v63
	v_mul_f32_e32 v104, v64, v50
	v_mul_f32_e32 v105, v65, v50
	v_add_f32_dpp v100, v100, v100 quad_perm:[1,0,3,2] row_mask:0xf bank_mask:0xf bound_ctrl:1
	v_mul_f32_e32 v106, v66, v50
	v_mul_f32_e32 v107, v67, v50
	v_add_f32_dpp v100, v100, v100 quad_perm:[2,3,0,1] row_mask:0xf bank_mask:0xf bound_ctrl:1
	v_fmac_f32_e32 v104, v0, v68
	v_fmac_f32_e32 v105, v1, v69
	v_add_f32_dpp v100, v100, v100 row_half_mirror row_mask:0xf bank_mask:0xf bound_ctrl:1
	v_fmac_f32_e32 v106, v2, v70
	v_fmac_f32_e32 v107, v3, v71
	v_add_f32_dpp v100, v100, v100 row_mirror row_mask:0xf bank_mask:0xf bound_ctrl:1
	v_fma_f32 v0, -v72, v100, v104
	v_fma_f32 v1, -v73, v100, v105
	v_fma_f32 v2, -v74, v100, v106
	v_fma_f32 v3, -v75, v100, v107
	v_mul_f32_e32 v101, v0, v76
	v_fmac_f32_e32 v101, v1, v77
	v_fmac_f32_e32 v101, v2, v78
	v_fmac_f32_e32 v101, v3, v79
	ds_write_b32 v33, v101 offset:10240
	ds_read_b128 v[60:63], v31 offset:15616
	ds_read_b128 v[64:67], v31 offset:16128
	ds_read_b128 v[68:71], v31 offset:15360
	ds_read_b128 v[72:75], v31 offset:15872
	ds_read_b128 v[76:79], v31 offset:16384
	s_waitcnt lgkmcnt(6)
	v_mul_f32_e32 v100, v0, v80
	v_fmac_f32_e32 v100, v1, v81
	v_fmac_f32_e32 v100, v2, v82
	v_fmac_f32_e32 v100, v3, v83
	v_mul_f32_e32 v104, v84, v51
	v_mul_f32_e32 v105, v85, v51
	v_add_f32_dpp v100, v100, v100 quad_perm:[1,0,3,2] row_mask:0xf bank_mask:0xf bound_ctrl:1
	v_mul_f32_e32 v106, v86, v51
	v_mul_f32_e32 v107, v87, v51
	v_add_f32_dpp v100, v100, v100 quad_perm:[2,3,0,1] row_mask:0xf bank_mask:0xf bound_ctrl:1
	v_fmac_f32_e32 v104, v0, v88
	v_fmac_f32_e32 v105, v1, v89
	v_add_f32_dpp v100, v100, v100 row_half_mirror row_mask:0xf bank_mask:0xf bound_ctrl:1
	v_fmac_f32_e32 v106, v2, v90
	v_fmac_f32_e32 v107, v3, v91
	v_add_f32_dpp v100, v100, v100 row_mirror row_mask:0xf bank_mask:0xf bound_ctrl:1
	v_fma_f32 v0, -v92, v100, v104
	v_fma_f32 v1, -v93, v100, v105
	v_fma_f32 v2, -v94, v100, v106
	v_fma_f32 v3, -v95, v100, v107
	v_mul_f32_e32 v101, v0, v96
	v_fmac_f32_e32 v101, v1, v97
	v_fmac_f32_e32 v101, v2, v98
	v_fmac_f32_e32 v101, v3, v99
	ds_write_b32 v33, v101 offset:11264
	ds_read_b128 v[80:83], v31 offset:16896
	ds_read_b128 v[84:87], v31 offset:17408
	ds_read_b128 v[88:91], v31 offset:16640
	ds_read_b128 v[92:95], v31 offset:17152
	ds_read_b128 v[96:99], v31 offset:17664
	s_waitcnt lgkmcnt(6)
; #define LAS __attribute__((address_space(3)))
; __device__ __forceinline__ float sum16(float x) { x = dpp_add<0xB1>(x); x = dpp_add<0x4E>(x); x = dpp_add<0x141>(x); x = dpp_add<0x140>(x); return x; }
; __device__ __forceinline__ void scan_step(f32x4& S, const ScanOps& o, LAS float* yp) {
;     f32x2 S0 = {S[0], S[1]}, S1 = {S[2], S[3]};
;     const f32x2 k0 = {o.kk[0], o.kk[1]}, k1 = {o.kk[2], o.kk[3]};
;     f32x2 t = S0 * k0; t = S1 * k1 + t;
;     const float sa = -sum16(t[0] + t[1]);
;     const f32x2 sav = {sa, sa}, vv = {o.v, o.v};
;     const f32x2 a0 = {o.ka[0], o.ka[1]}, a1 = {o.ka[2], o.ka[3]}, p0 = {o.kp[0], o.kp[1]}, p1 = {o.kp[2], o.kp[3]}, w0 = {o.w[0], o.w[1]}, w1 = {o.w[2], o.w[3]};
;     f32x2 u0 = a0 * sav; u0 = p0 * vv + u0; S0 = S0 * w0 + u0;
;     f32x2 u1 = a1 * sav; u1 = p1 * vv + u1; S1 = S1 * w1 + u1;
;     const f32x2 r0 = {o.rr[0], o.rr[1]}, r1 = {o.rr[2], o.rr[3]};
;     f32x2 y = S0 * r0; y = S1 * r1 + y;
;     *yp = y[0] + y[1];
;     S = (f32x4){S0[0], S0[1], S1[0], S1[1]};
; __device__ __forceinline__ void scan_unit(const Ctx& p, int chain, int rq, LAS unsigned char* lds) {
;     ...
;         for (int ci = 0; ci < nch; ++ci) {
;             __syncthreads();
;             const LAS float* OP = B0 + (ci & 1) * SBUF_F + 4 * cl;
;             const LAS float* VP = B0 + (ci & 1) * SBUF_F + SCH * 320 + il * 16;
;             LAS float* Y = YB + (ci & 1) * YP_F + il * 16 + cl;
;             ScanOps oa, ob;
;             scan_load(oa, OP, VP, 0);
;             f32x2 vv = *(const LAS f32x2*)VP;
; #pragma unroll 1
;             for (int t = 0; t < SCH; t += 2) {
;                 scan_load(ob, OP, VP, t + 1);
;                 oa.v = vv[0]; ob.v = vv[1];
;                 scan_step(S, oa, Y + t * 256);
;                 scan_load(oa, OP, VP, (t + 2) & (SCH - 1));
;                 vv = *(const LAS f32x2*)(VP + ((t + 2) & (SCH - 1)));
;                 scan_step(S, ob, Y + (t + 1) * 256);
;             }
;         }
;         __syncthreads();
;         *(f32x4*)sg = S;
	v_mul_f32_e32 v100, v0, v60
	v_fmac_f32_e32 v100, v1, v61
	v_fmac_f32_e32 v100, v2, v62
	v_fmac_f32_e32 v100, v3, v63
	v_mul_f32_e32 v104, v64, v52
	v_mul_f32_e32 v105, v65, v52
	v_add_f32_dpp v100, v100, v100 quad_perm:[1,0,3,2] row_mask:0xf bank_mask:0xf bound_ctrl:1
	v_mul_f32_e32 v106, v66, v52
	v_mul_f32_e32 v107, v67, v52
	v_add_f32_dpp v100, v100, v100 quad_perm:[2,3,0,1] row_mask:0xf bank_mask:0xf bound_ctrl:1
	v_fmac_f32_e32 v104, v0, v68
	v_fmac_f32_e32 v105, v1, v69
	v_add_f32_dpp v100, v100, v100 row_half_mirror row_mask:0xf bank_mask:0xf bound_ctrl:1
	v_fmac_f32_e32 v106, v2, v70
	v_fmac_f32_e32 v107, v3, v71
	v_add_f32_dpp v100, v100, v100 row_mirror row_mask:0xf bank_mask:0xf bound_ctrl:1
	v_fma_f32 v0, -v72, v100, v104
	v_fma_f32 v1, -v73, v100, v105
	v_fma_f32 v2, -v74, v100, v106
	v_fma_f32 v3, -v75, v100, v107
	v_mul_f32_e32 v101, v0, v76
	v_fmac_f32_e32 v101, v1, v77
	v_fmac_f32_e32 v101, v2, v78
	v_fmac_f32_e32 v101, v3, v79
	ds_write_b32 v33, v101 offset:12288
	ds_read_b128 v[60:63], v31 offset:18176
	ds_read_b128 v[64:67], v31 offset:18688
	ds_read_b128 v[68:71], v31 offset:17920
	ds_read_b128 v[72:75], v31 offset:18432
	ds_read_b128 v[76:79], v31 offset:18944
	s_waitcnt lgkmcnt(6)
	v_mul_f32_e32 v100, v0, v80
	v_fmac_f32_e32 v100, v1, v81
	v_fmac_f32_e32 v100, v2, v82
	v_fmac_f32_e32 v100, v3, v83
	v_mul_f32_e32 v104, v84, v53
	v_mul_f32_e32 v105, v85, v53
	v_add_f32_dpp v100, v100, v100 quad_perm:[1,0,3,2] row_mask:0xf bank_mask:0xf bound_ctrl:1
	v_mul_f32_e32 v106, v86, v53
	v_mul_f32_e32 v107, v87, v53
	v_add_f32_dpp v100, v100, v100 quad_perm:[2,3,0,1] row_mask:0xf bank_mask:0xf bound_ctrl:1
	v_fmac_f32_e32 v104, v0, v88
	v_fmac_f32_e32 v105, v1, v89
	v_add_f32_dpp v100, v100, v100 row_half_mirror row_mask:0xf bank_mask:0xf bound_ctrl:1
	v_fmac_f32_e32 v106, v2, v90
	v_fmac_f32_e32 v107, v3, v91
	v_add_f32_dpp v100, v100, v100 row_mirror row_mask:0xf bank_mask:0xf bound_ctrl:1
	v_fma_f32 v0, -v92, v100, v104
	v_fma_f32 v1, -v93, v100, v105
	v_fma_f32 v2, -v94, v100, v106
	v_fma_f32 v3, -v95, v100, v107
	v_mul_f32_e32 v101, v0, v96
	v_fmac_f32_e32 v101, v1, v97
	v_fmac_f32_e32 v101, v2, v98
	v_fmac_f32_e32 v101, v3, v99
	ds_write_b32 v33, v101 offset:13312
	ds_read_b128 v[80:83], v31 offset:19456
	ds_read_b128 v[84:87], v31 offset:19968
	ds_read_b128 v[88:91], v31 offset:19200
	ds_read_b128 v[92:95], v31 offset:19712
	ds_read_b128 v[96:99], v31 offset:20224
	s_waitcnt lgkmcnt(6)
	v_mul_f32_e32 v100, v0, v60
	v_fmac_f32_e32 v100, v1, v61
	v_fmac_f32_e32 v100, v2, v62
	v_fmac_f32_e32 v100, v3, v63
	v_mul_f32_e32 v104, v64, v54
	v_mul_f32_e32 v105, v65, v54
	v_add_f32_dpp v100, v100, v100 quad_perm:[1,0,3,2] row_mask:0xf bank_mask:0xf bound_ctrl:1
	v_mul_f32_e32 v106, v66, v54
	v_mul_f32_e32 v107, v67, v54
	v_add_f32_dpp v100, v100, v100 quad_perm:[2,3,0,1] row_mask:0xf bank_mask:0xf bound_ctrl:1
	v_fmac_f32_e32 v104, v0, v68
	v_fmac_f32_e32 v105, v1, v69
	v_add_f32_dpp v100, v100, v100 row_half_mirror row_mask:0xf bank_mask:0xf bound_ctrl:1
	v_fmac_f32_e32 v106, v2, v70
	v_fmac_f32_e32 v107, v3, v71
	v_add_f32_dpp v100, v100, v100 row_mirror row_mask:0xf bank_mask:0xf bound_ctrl:1
	v_fma_f32 v0, -v72, v100, v104
	v_fma_f32 v1, -v73, v100, v105
	v_fma_f32 v2, -v74, v100, v106
	v_fma_f32 v3, -v75, v100, v107
	v_mul_f32_e32 v101, v0, v76
	v_fmac_f32_e32 v101, v1, v77
	v_fmac_f32_e32 v101, v2, v78
	v_fmac_f32_e32 v101, v3, v79
	ds_write_b32 v33, v101 offset:14336
	s_waitcnt lgkmcnt(1)
	v_mul_f32_e32 v100, v0, v80
	v_fmac_f32_e32 v100, v1, v81
	v_fmac_f32_e32 v100, v2, v82
	v_fmac_f32_e32 v100, v3, v83
	v_mul_f32_e32 v104, v84, v55
	v_mul_f32_e32 v105, v85, v55
	v_add_f32_dpp v100, v100, v100 quad_perm:[1,0,3,2] row_mask:0xf bank_mask:0xf bound_ctrl:1
	v_mul_f32_e32 v106, v86, v55
	v_mul_f32_e32 v107, v87, v55
	v_add_f32_dpp v100, v100, v100 quad_perm:[2,3,0,1] row_mask:0xf bank_mask:0xf bound_ctrl:1
	v_fmac_f32_e32 v104, v0, v88
	v_fmac_f32_e32 v105, v1, v89
	v_add_f32_dpp v100, v100, v100 row_half_mirror row_mask:0xf bank_mask:0xf bound_ctrl:1
	v_fmac_f32_e32 v106, v2, v90
	v_fmac_f32_e32 v107, v3, v91
	v_add_f32_dpp v100, v100, v100 row_mirror row_mask:0xf bank_mask:0xf bound_ctrl:1
	v_fma_f32 v0, -v92, v100, v104
	v_fma_f32 v1, -v93, v100, v105
	v_fma_f32 v2, -v94, v100, v106
	v_fma_f32 v3, -v95, v100, v107
	v_mul_f32_e32 v101, v0, v96
	v_fmac_f32_e32 v101, v1, v97
	v_fmac_f32_e32 v101, v2, v98
	v_fmac_f32_e32 v101, v3, v99
	ds_write_b32 v33, v101 offset:15360
	s_add_i32 s10, s10, 1
	s_cmpk_eq_i32 s10, 0x100
	s_cbranch_scc0 .LBB0_1714
	s_setprio 0
	s_lshl_b32 s8, s28, 12
	v_lshl_or_b32 v4, v27, 8, s8
	v_mov_b32_e32 v5, 0
	v_lshl_add_u64 v[6:7], s[2:3], 0, v[4:5]
	v_lshlrev_b32_e32 v4, 2, v26
	v_lshl_add_u64 v[4:5], v[6:7], 0, v[4:5]
	v_add_co_u32_e32 v4, vcc, 0x8080000, v4
	s_mov_b64 s[2:3], 0
	s_nop 0
	v_addc_co_u32_e32 v5, vcc, 0, v5, vcc
	s_waitcnt lgkmcnt(0)
	s_barrier
	global_store_dwordx4 v[4:5], v[0:3], off
